# HGRN E-wave loop: removed no-op vmcnt waits and replaced 64-bit address add/addc triples by chained v_lshl_add_u64 (on top of epilogue splits, rstd lane-distribution, conv nw batching)
# speedup vs baseline: 1.0097x; 1.0077x over previous
; __device__ __forceinline__ void hgrn_unit(LAS unsigned char* lds, int b, int h, int vs, const bf16* QR, const _Float16* LF, const bf16* IO, bf16* OR_) {
;     ...
;         const int ew = wid, t0 = 16 * ew;
;         const unsigned* lp = (const unsigned*)(LF + (rowbase + t0) * 1024 + h * 128) + lane;
;         const unsigned* qp = (const unsigned*)(QR + (rowbase + t0) * 1024 + h * 128) + lane;
;         const int et = ew * 64 + lane, vrow = et >> 2, c8 = et & 3;
;         const v4u* vp = (const v4u*)(IO + (rowbase + vrow) * 1024 + h * 128 + vs * 32 + 8 * c8);
;         unsigned clf[16], cq[16], nlf[16], nq[16]; v4u cv, nv;
; #pragma unroll
;         for (int i = 0; i < 16; ++i) { clf[i] = lp[i * 512]; cq[i] = qp[i * 512]; nlf[i] = 0u; nq[i] = 0u; }
;         cv = *vp; nv = cv;
.LBB0_1546:
	s_and_b64 vcc, exec, s[0:1]
	s_cbranch_vccz .LBB0_1415
	s_mov_b64 s[98:99], 0x1000
	s_lshl_b32 s0, s3, 4
	s_ashr_i32 s1, s0, 31
	s_add_u32 s8, s86, s0
	s_addc_u32 s9, s87, s1
	s_lshl_b64 s[8:9], s[8:9], 11
	s_add_u32 s1, s55, s8
	s_addc_u32 s11, s56, s9
	s_lshl_b32 s42, s37, 8
	s_add_u32 s10, s1, s42
	s_addc_u32 s11, s11, 0
	s_add_u32 s1, s57, s8
	s_addc_u32 s9, s58, s9
	s_add_u32 s8, s1, s42
	v_mov_b32_e32 v2, s39
	s_movk_i32 s1, 0xffc0
	v_and_b32_e32 v34, 63, v184
	v_bfi_b32 v36, s1, v2, v184
	v_lshlrev_b32_e32 v0, 2, v34
	v_ashrrev_i32_e32 v6, 2, v36
	v_lshl_add_u64 v[10:11], s[10:11], 0, v[0:1]
	v_ashrrev_i32_e32 v7, 31, v6
	v_lshlrev_b32_e32 v4, 3, v184
	s_movk_i32 s1, 0x1000
	v_lshl_add_u64 v[2:3], s[86:87], 0, v[6:7]
	v_and_b32_e32 v7, 24, v4
	v_add_co_u32_e32 v4, vcc, s1, v10
	s_addc_u32 s9, s9, 0
	s_nop 0
	v_addc_co_u32_e32 v5, vcc, 0, v11, vcc
	v_add_co_u32_e32 v8, vcc, s49, v10
	v_lshl_add_u64 v[12:13], s[8:9], 0, v[0:1]
	s_nop 0
	v_addc_co_u32_e32 v9, vcc, 0, v11, vcc
	v_add_co_u32_e32 v14, vcc, s1, v12
	global_load_dword v41, v0, s[10:11]
	global_load_dword v39, v0, s[8:9]
	global_load_dword v43, v0, s[10:11] offset:2048
	global_load_dword v37, v0, s[8:9] offset:2048
	v_addc_co_u32_e32 v15, vcc, 0, v13, vcc
	v_add_co_u32_e32 v32, vcc, s49, v12
	s_movk_i32 s8, 0x3000
	s_nop 0
	v_addc_co_u32_e32 v33, vcc, 0, v13, vcc
	global_load_dword v47, v[8:9], off offset:-4096
	global_load_dword v53, v[32:33], off offset:-4096
	global_load_dword v51, v[4:5], off offset:2048
	global_load_dword v54, v[14:15], off offset:2048
	global_load_dword v49, v[8:9], off
	global_load_dword v35, v[32:33], off
	global_load_dword v45, v[8:9], off offset:2048
	s_nop 0
	global_load_dword v33, v[32:33], off offset:2048
	v_add_co_u32_e32 v4, vcc, s8, v10
	s_movk_i32 s1, 0x4000
	s_nop 0
	v_addc_co_u32_e32 v5, vcc, 0, v11, vcc
	v_add_co_u32_e32 v8, vcc, s1, v10
	v_lshlrev_b64 v[2:3], 11, v[2:3]
	s_nop 0
	v_addc_co_u32_e32 v9, vcc, 0, v11, vcc
	v_add_co_u32_e32 v14, vcc, s8, v12
	global_load_dword v55, v[8:9], off offset:-4096
	s_nop 0
	v_addc_co_u32_e32 v15, vcc, 0, v13, vcc
	v_add_co_u32_e32 v60, vcc, s1, v12
	s_movk_i32 s1, 0x5000
	s_nop 0
	v_addc_co_u32_e32 v61, vcc, 0, v13, vcc
	s_waitcnt lgkmcnt(4)
	global_load_dword v56, v[60:61], off offset:-4096
	global_load_dword v58, v[4:5], off offset:2048
	global_load_dword v57, v[14:15], off offset:2048
	global_load_dword v63, v[8:9], off
	global_load_dword v65, v[60:61], off
	global_load_dword v59, v[8:9], off offset:2048
	global_load_dword v66, v[60:61], off offset:2048
	v_add_co_u32_e32 v4, vcc, s1, v10
	v_lshl_add_u64 v[2:3], s[4:5], 0, v[2:3]
	s_nop 0
	v_addc_co_u32_e32 v5, vcc, 0, v11, vcc
	v_add_co_u32_e32 v8, vcc, s48, v10
	v_lshl_add_u64 v[2:3], v[2:3], 0, s[42:43]
	s_nop 0
	v_addc_co_u32_e32 v9, vcc, 0, v11, vcc
	v_add_co_u32_e32 v14, vcc, s1, v12
	global_load_dword v64, v[8:9], off offset:-4096
	s_nop 0
	v_addc_co_u32_e32 v15, vcc, 0, v13, vcc
	v_add_co_u32_e32 v60, vcc, s48, v12
	s_lshl_b32 s42, s36, 6
	s_nop 0
	v_addc_co_u32_e32 v61, vcc, 0, v13, vcc
	global_load_dword v71, v[60:61], off offset:-4096
	global_load_dword v70, v[4:5], off offset:2048
	global_load_dword v72, v[14:15], off offset:2048
	global_load_dword v69, v[8:9], off
	global_load_dword v73, v[60:61], off
	global_load_dword v67, v[8:9], off offset:2048
	global_load_dword v74, v[60:61], off offset:2048
	v_add_co_u32_e32 v4, vcc, s78, v10
	v_lshl_add_u64 v[2:3], v[2:3], 0, s[42:43]
	s_nop 0
	v_addc_co_u32_e32 v5, vcc, 0, v11, vcc
	v_add_co_u32_e32 v8, vcc, s78, v12
	v_lshlrev_b32_e32 v0, 1, v7
	s_nop 0
	v_addc_co_u32_e32 v9, vcc, 0, v13, vcc
	global_load_dword v68, v[4:5], off
	global_load_dword v75, v[8:9], off
	global_load_dword v81, v[4:5], off offset:2048
	global_load_dword v62, v[8:9], off offset:2048
	v_lshl_add_u64 v[14:15], v[2:3], 0, v[0:1]
	global_load_dwordx4 v[2:5], v[14:15], off
	s_cmp_gt_i32 s3, 0
	s_cselect_b64 s[8:9], -1, 0
	s_cmp_gt_i32 s3, 1
	v_lshlrev_b32_e32 v8, 3, v34
	s_cselect_b64 s[10:11], -1, 0
	s_cmp_eq_u32 s3, 3
	s_mulk_i32 s3, 0x440
	v_add_u32_e32 v110, s79, v8
	v_add_u32_e32 v111, s72, v8
	v_or_b32_e32 v8, s3, v34
	v_lshl_add_u32 v112, v8, 2, 0
	v_mul_u32_u24_e32 v8, 0x90, v34
	v_lshl_add_u32 v6, v6, 1, 0
	s_cselect_b64 s[12:13], -1, 0
	s_cmp_lt_u32 s39, 64
	v_mul_u32_u24_e32 v7, 0x90, v7
	v_add_lshl_u32 v8, s0, v8, 1
	v_lshl_add_u32 v0, v36, 3, s79
	s_cselect_b64 s[14:15], -1, 0
	v_mov_b32_e32 v115, 0
	s_mov_b32 s0, 32
	v_add_u32_e32 v113, 0, v8
	v_add_u32_e32 v114, v6, v7
	v_mov_b32_e32 v116, 0
	v_mov_b32_e32 v119, 0
	v_mov_b32_e32 v120, 0
	v_mov_b32_e32 v123, 0
	v_mov_b32_e32 v124, 0
	v_mov_b32_e32 v127, 0
	v_mov_b32_e32 v128, 0
	v_mov_b32_e32 v131, 0
	v_mov_b32_e32 v132, 0
	v_mov_b32_e32 v135, 0
	v_mov_b32_e32 v136, 0
	v_mov_b32_e32 v139, 0
	v_mov_b32_e32 v140, 0
	v_mov_b32_e32 v143, 0
	v_mov_b32_e32 v144, 0
	v_mov_b32_e32 v117, 0
	v_mov_b32_e32 v118, 0
	v_mov_b32_e32 v121, 0
	v_mov_b32_e32 v122, 0
	v_mov_b32_e32 v125, 0
	v_mov_b32_e32 v126, 0
	v_mov_b32_e32 v129, 0
	v_mov_b32_e32 v130, 0
	v_mov_b32_e32 v133, 0
	v_mov_b32_e32 v134, 0
	v_mov_b32_e32 v137, 0
	v_mov_b32_e32 v138, 0
	v_mov_b32_e32 v141, 0
	v_mov_b32_e32 v142, 0
	v_mov_b32_e32 v145, 0
	v_mov_b32_e32 v146, 0
	s_branch .LBB0_1549
; #define LAS __attribute__((address_space(3)))
; #define HG_BAR() asm volatile("s_waitcnt lgkmcnt(0)\n\ts_barrier" ::: "memory")
; __device__ __forceinline__ void hgrn_unit(LAS unsigned char* lds, int b, int h, int vs, const bf16* QR, const _Float16* LF, const bf16* IO, bf16* OR_) {
;     ...
;             if (n + 1 < NCH) { lp += 64 * 512; qp += 64 * 512; vp += 64 * 128;
; #pragma unroll
;                 for (int i = 0; i < 16; ++i) { nlf[i] = lp[i * 512]; nq[i] = qp[i * 512]; }
;                 nv = *vp; }
;     ...
;             { LAS bf16* vt = (LAS bf16*)(lds + OFF_VT) + (8 * c8) * TS + vrow;
;               vt[0 * TS] = (bf16)(cv.x & 0xffffu); vt[1 * TS] = (bf16)(cv.x >> 16); vt[2 * TS] = (bf16)(cv.y & 0xffffu); vt[3 * TS] = (bf16)(cv.y >> 16);
;               vt[4 * TS] = (bf16)(cv.z & 0xffffu); vt[5 * TS] = (bf16)(cv.z >> 16); vt[6 * TS] = (bf16)(cv.w & 0xffffu); vt[7 * TS] = (bf16)(cv.w >> 16); }
; #pragma unroll
;             for (int i = 0; i < 16; ++i) { clf[i] = nlf[i]; cq[i] = nq[i]; }
;             cv = nv;
;             HG_BAR();
.LBB0_1548:
	ds_write_b16 v114, v2 offset:53248
	ds_write_b16_d16_hi v114, v2 offset:53392
	ds_write_b16 v114, v3 offset:53536
	ds_write_b16_d16_hi v114, v3 offset:53680
	ds_write_b16 v114, v4 offset:53824
	ds_write_b16_d16_hi v114, v4 offset:53968
	ds_write_b16 v114, v5 offset:54112
	ds_write_b16_d16_hi v114, v5 offset:54256
	s_waitcnt lgkmcnt(0)
	s_barrier
	s_add_i32 s0, s0, -1
	s_waitcnt vmcnt(0)
	v_mov_b64_e32 v[2:3], v[6:7]
	s_cmp_eq_u32 s0, 0
	v_mov_b32_e32 v39, v115
	v_mov_b32_e32 v37, v116
	v_mov_b32_e32 v53, v119
	v_mov_b32_e32 v54, v120
	v_mov_b32_e32 v35, v123
	v_mov_b32_e32 v33, v124
	v_mov_b32_e32 v56, v127
	v_mov_b32_e32 v57, v128
	v_mov_b32_e32 v65, v131
	v_mov_b32_e32 v66, v132
	v_mov_b32_e32 v71, v135
	v_mov_b32_e32 v72, v136
	v_mov_b32_e32 v73, v139
	v_mov_b32_e32 v74, v140
	v_mov_b32_e32 v75, v143
	v_mov_b32_e32 v62, v144
	v_mov_b32_e32 v41, v117
	v_mov_b32_e32 v43, v118
	v_mov_b32_e32 v47, v121
	v_mov_b32_e32 v51, v122
	v_mov_b32_e32 v49, v125
	v_mov_b32_e32 v45, v126
	v_mov_b32_e32 v55, v129
	v_mov_b32_e32 v58, v130
	v_mov_b32_e32 v63, v133
	v_mov_b32_e32 v59, v134
	v_mov_b32_e32 v64, v137
	v_mov_b32_e32 v70, v138
	v_mov_b32_e32 v69, v141
	v_mov_b32_e32 v67, v142
	v_mov_b32_e32 v68, v145
	v_mov_b32_e32 v81, v146
	v_mov_b64_e32 v[4:5], v[8:9]
	s_cbranch_scc1 .LBB0_1414
.LBB0_1549:
	s_cmp_eq_u32 s0, 1
	s_cbranch_scc1 .LBB0_1551
	v_lshl_add_u64 v[6:7], v[10:11], 0, s[74:75]
	v_lshl_add_u64 v[8:9], v[12:13], 0, s[74:75]
	global_load_dword v117, v[6:7], off
	global_load_dword v118, v[6:7], off offset:2048
	global_load_dword v115, v[8:9], off
	global_load_dword v116, v[8:9], off offset:2048
	v_lshl_add_u64 v[6:7], v[6:7], 0, s[98:99]
	v_lshl_add_u64 v[8:9], v[8:9], 0, s[98:99]
	global_load_dword v121, v[6:7], off
	global_load_dword v122, v[6:7], off offset:2048
	global_load_dword v119, v[8:9], off
	global_load_dword v120, v[8:9], off offset:2048
	v_lshl_add_u64 v[6:7], v[6:7], 0, s[98:99]
	v_lshl_add_u64 v[8:9], v[8:9], 0, s[98:99]
	global_load_dword v125, v[6:7], off
	global_load_dword v126, v[6:7], off offset:2048
	global_load_dword v123, v[8:9], off
	global_load_dword v124, v[8:9], off offset:2048
	v_lshl_add_u64 v[6:7], v[6:7], 0, s[98:99]
	v_lshl_add_u64 v[8:9], v[8:9], 0, s[98:99]
	global_load_dword v129, v[6:7], off
	global_load_dword v130, v[6:7], off offset:2048
	global_load_dword v127, v[8:9], off
	global_load_dword v128, v[8:9], off offset:2048
	v_lshl_add_u64 v[6:7], v[6:7], 0, s[98:99]
	v_lshl_add_u64 v[8:9], v[8:9], 0, s[98:99]
	global_load_dword v133, v[6:7], off
	global_load_dword v134, v[6:7], off offset:2048
	global_load_dword v131, v[8:9], off
	global_load_dword v132, v[8:9], off offset:2048
	v_lshl_add_u64 v[6:7], v[6:7], 0, s[98:99]
	v_lshl_add_u64 v[8:9], v[8:9], 0, s[98:99]
	global_load_dword v137, v[6:7], off
	global_load_dword v138, v[6:7], off offset:2048
	global_load_dword v135, v[8:9], off
	global_load_dword v136, v[8:9], off offset:2048
	v_lshl_add_u64 v[6:7], v[6:7], 0, s[98:99]
	v_lshl_add_u64 v[8:9], v[8:9], 0, s[98:99]
	global_load_dword v141, v[6:7], off
	global_load_dword v142, v[6:7], off offset:2048
	global_load_dword v139, v[8:9], off
	global_load_dword v140, v[8:9], off offset:2048
	v_lshl_add_u64 v[6:7], v[6:7], 0, s[98:99]
	v_lshl_add_u64 v[8:9], v[8:9], 0, s[98:99]
	global_load_dword v145, v[6:7], off
	global_load_dword v146, v[6:7], off offset:2048
	global_load_dword v143, v[8:9], off
	global_load_dword v144, v[8:9], off offset:2048
	v_lshl_add_u64 v[10:11], v[10:11], 0, s[74:75]
	v_lshl_add_u64 v[12:13], v[12:13], 0, s[74:75]
	v_lshl_add_u64 v[6:7], v[14:15], 0, s[74:75]
	global_load_dwordx4 v[6:9], v[6:7], off
	v_lshl_add_u64 v[14:15], v[14:15], 0, s[74:75]
	s_branch .LBB0_1552

; #define LAS __attribute__((address_space(3)))
; #define HG_BAR() asm volatile("s_waitcnt lgkmcnt(0)\n\ts_barrier" ::: "memory")
; __device__ __forceinline__ void hgrn_unit(LAS unsigned char* lds, int b, int h, int vs, const bf16* QR, const _Float16* LF, const bf16* IO, bf16* OR_) {
;     ...
;             float qa[2][16], kb[2][16], tot[2];
; #pragma unroll
;             for (int e = 0; e < 2; ++e) { float run = 1.f;
; #pragma unroll
;                 for (int i = 0; i < 16; ++i) { const unsigned short hb = (unsigned short)(e ? (clf[i] >> 16) : (clf[i] & 0xffffu)); const float kk = (float)__builtin_bit_cast(_Float16, hb);
;                     run *= (1.f - kk); const float q = e ? bfhi(cq[i]) : bflo(cq[i]);
;                     qa[e][i] = q * run; kb[e][i] = kk * __builtin_amdgcn_rcpf(run); }
;                 tot[e] = run; }
;             ((LAS f32x2_m*)(lds + OFF_TOT))[ew * 64 + lane] = (f32x2_m){tot[0], tot[1]};
;             HG_BAR();
.LBB0_1552:
	s_waitcnt vmcnt(33)
	v_cvt_f32_f16_sdwa v159, v43 dst_sel:DWORD dst_unused:UNUSED_PAD src0_sel:WORD_1
	v_cvt_f32_f16_e32 v158, v41
	v_cvt_f32_f16_sdwa v163, v41 dst_sel:DWORD dst_unused:UNUSED_PAD src0_sel:WORD_1
	v_cvt_f32_f16_e32 v162, v43
	v_cvt_f32_f16_sdwa v167, v47 dst_sel:DWORD dst_unused:UNUSED_PAD src0_sel:WORD_1
	v_cvt_f32_f16_e32 v166, v47
	v_cvt_f32_f16_sdwa v177, v51 dst_sel:DWORD dst_unused:UNUSED_PAD src0_sel:WORD_1
	v_cvt_f32_f16_e32 v176, v51
	v_cvt_f32_f16_sdwa v181, v49 dst_sel:DWORD dst_unused:UNUSED_PAD src0_sel:WORD_1
	v_cvt_f32_f16_e32 v180, v49
	v_pk_add_f32 v[160:161], v[158:159], 1.0 op_sel_hi:[1,0] neg_lo:[1,0] neg_hi:[1,0]
	v_pk_add_f32 v[168:169], v[162:163], 1.0 op_sel_hi:[1,0] neg_lo:[1,0] neg_hi:[1,0]
	v_cvt_f32_f16_sdwa v191, v45 dst_sel:DWORD dst_unused:UNUSED_PAD src0_sel:WORD_1
	v_cvt_f32_f16_e32 v190, v45
	v_pk_mul_f32 v[170:171], v[168:169], v[160:161]
	v_pk_add_f32 v[76:77], v[166:167], 1.0 op_sel_hi:[1,0] neg_lo:[1,0] neg_hi:[1,0]
	v_cvt_f32_f16_sdwa v109, v55 dst_sel:DWORD dst_unused:UNUSED_PAD src0_sel:WORD_1
	v_cvt_f32_f16_e32 v108, v55
	v_pk_mul_f32 v[174:175], v[170:171], v[76:77]
	v_pk_add_f32 v[76:77], v[176:177], 1.0 op_sel_hi:[1,0] neg_lo:[1,0] neg_hi:[1,0]
	v_cvt_f32_f16_sdwa v197, v58 dst_sel:DWORD dst_unused:UNUSED_PAD src0_sel:WORD_1
	v_cvt_f32_f16_e32 v196, v58
	v_pk_mul_f32 v[182:183], v[174:175], v[76:77]
	v_pk_add_f32 v[76:77], v[180:181], 1.0 op_sel_hi:[1,0] neg_lo:[1,0] neg_hi:[1,0]
	v_cvt_f32_f16_sdwa v105, v63 dst_sel:DWORD dst_unused:UNUSED_PAD src0_sel:WORD_1
	v_cvt_f32_f16_e32 v104, v63
	v_pk_mul_f32 v[186:187], v[182:183], v[76:77]
	v_pk_add_f32 v[76:77], v[190:191], 1.0 op_sel_hi:[1,0] neg_lo:[1,0] neg_hi:[1,0]
	v_cvt_f32_f16_sdwa v103, v59 dst_sel:DWORD dst_unused:UNUSED_PAD src0_sel:WORD_1
	v_cvt_f32_f16_e32 v102, v59
	v_lshlrev_b32_e32 v78, 16, v54
	v_and_b32_e32 v79, 0xffff0000, v54
	v_pk_mul_f32 v[192:193], v[186:187], v[76:77]
	v_pk_add_f32 v[54:55], v[108:109], 1.0 op_sel_hi:[1,0] neg_lo:[1,0] neg_hi:[1,0]
	v_cvt_f32_f16_sdwa v87, v64 dst_sel:DWORD dst_unused:UNUSED_PAD src0_sel:WORD_1
	v_cvt_f32_f16_e32 v86, v64
	v_pk_mul_f32 v[198:199], v[192:193], v[54:55]
	v_pk_add_f32 v[54:55], v[196:197], 1.0 op_sel_hi:[1,0] neg_lo:[1,0] neg_hi:[1,0]
	v_cvt_f32_f16_sdwa v83, v70 dst_sel:DWORD dst_unused:UNUSED_PAD src0_sel:WORD_1
	v_cvt_f32_f16_e32 v82, v70
	v_lshlrev_b32_e32 v94, 16, v39
	v_lshlrev_b32_e32 v40, 16, v72
	v_lshlrev_b32_e32 v38, 16, v73
	v_and_b32_e32 v100, 0xffff0000, v39
	v_and_b32_e32 v41, 0xffff0000, v72
	v_and_b32_e32 v39, 0xffff0000, v73
	v_pk_mul_f32 v[202:203], v[198:199], v[54:55]
	v_pk_add_f32 v[54:55], v[104:105], 1.0 op_sel_hi:[1,0] neg_lo:[1,0] neg_hi:[1,0]
	v_cvt_f32_f16_sdwa v73, v69 dst_sel:DWORD dst_unused:UNUSED_PAD src0_sel:WORD_1
	v_cvt_f32_f16_e32 v72, v69
	v_lshlrev_b32_e32 v42, 16, v71
	v_and_b32_e32 v43, 0xffff0000, v71
	v_pk_mul_f32 v[206:207], v[202:203], v[54:55]
	v_pk_add_f32 v[54:55], v[102:103], 1.0 op_sel_hi:[1,0] neg_lo:[1,0] neg_hi:[1,0]
	v_cvt_f32_f16_sdwa v71, v67 dst_sel:DWORD dst_unused:UNUSED_PAD src0_sel:WORD_1
	v_cvt_f32_f16_e32 v70, v67
	v_pk_mul_f32 v[106:107], v[206:207], v[54:55]
	v_pk_add_f32 v[54:55], v[86:87], 1.0 op_sel_hi:[1,0] neg_lo:[1,0] neg_hi:[1,0]
	v_lshlrev_b32_e32 v50, 16, v56
	v_pk_mul_f32 v[92:93], v[106:107], v[54:55]
	v_pk_add_f32 v[54:55], v[82:83], 1.0 op_sel_hi:[1,0] neg_lo:[1,0] neg_hi:[1,0]
	v_lshlrev_b32_e32 v48, 16, v57
	v_pk_mul_f32 v[88:89], v[92:93], v[54:55]
	v_pk_add_f32 v[54:55], v[72:73], 1.0 op_sel_hi:[1,0] neg_lo:[1,0] neg_hi:[1,0]
	v_and_b32_e32 v51, 0xffff0000, v56
	v_and_b32_e32 v49, 0xffff0000, v57
	v_pk_mul_f32 v[76:77], v[88:89], v[54:55]
	v_pk_add_f32 v[54:55], v[70:71], 1.0 op_sel_hi:[1,0] neg_lo:[1,0] neg_hi:[1,0]
	v_cvt_f32_f16_sdwa v57, v68 dst_sel:DWORD dst_unused:UNUSED_PAD src0_sel:WORD_1
	v_cvt_f32_f16_e32 v56, v68
	v_lshlrev_b32_e32 v156, 16, v37
	v_lshlrev_b32_e32 v60, 16, v35
	v_lshlrev_b32_e32 v36, 16, v74
	v_lshlrev_b32_e32 v34, 16, v75
	v_and_b32_e32 v157, 0xffff0000, v37
	v_and_b32_e32 v61, 0xffff0000, v35
	v_and_b32_e32 v37, 0xffff0000, v74
	v_and_b32_e32 v35, 0xffff0000, v75
	v_pk_mul_f32 v[74:75], v[76:77], v[54:55]
	v_cvt_f32_f16_sdwa v55, v81 dst_sel:DWORD dst_unused:UNUSED_PAD src0_sel:WORD_1
	v_cvt_f32_f16_e32 v54, v81
	v_pk_add_f32 v[58:59], v[56:57], 1.0 op_sel_hi:[1,0] neg_lo:[1,0] neg_hi:[1,0]
	v_lshlrev_b32_e32 v44, 16, v66
	v_and_b32_e32 v45, 0xffff0000, v66
	v_pk_mul_f32 v[66:67], v[74:75], v[58:59]
	v_pk_add_f32 v[58:59], v[54:55], 1.0 op_sel_hi:[1,0] neg_lo:[1,0] neg_hi:[1,0]
	v_lshlrev_b32_e32 v90, 16, v53
	v_pk_mul_f32 v[58:59], v[66:67], v[58:59]
	ds_write_b64 v0, v[58:59]
	s_waitcnt lgkmcnt(0)
	s_barrier
; #define LAS __attribute__((address_space(3)))
; __device__ __forceinline__ unsigned pkbf(float lo, float hi) { const f32x2_m v = {lo, hi}; const bf16x2_m b = __builtin_convertvector(v, bf16x2_m); return __builtin_bit_cast(unsigned, b); }
; __device__ __forceinline__ void hgrn_unit(LAS unsigned char* lds, int b, int h, int vs, const bf16* QR, const _Float16* LF, const bf16* IO, bf16* OR_) {
;     ...
;             float eoff[2], ieoff[2], eGl[2];
;             { const f32x2_m t0v = ((LAS f32x2_m*)(lds + OFF_TOT))[lane], t1v = ((LAS f32x2_m*)(lds + OFF_TOT))[64 + lane], t2v = ((LAS f32x2_m*)(lds + OFF_TOT))[128 + lane], t3v = ((LAS f32x2_m*)(lds + OFF_TOT))[192 + lane];
; #pragma unroll
;               for (int e = 0; e < 2; ++e) { const float off = (ew > 0 ? t0v[e] : 1.f) * (ew > 1 ? t1v[e] : 1.f) * (ew > 2 ? t2v[e] : 1.f);
;                   eoff[e] = off; ieoff[e] = __builtin_amdgcn_rcpf(off); eGl[e] = (t0v[e] * t1v[e]) * (t2v[e] * t3v[e]); } }
;             unsigned klp[2][8];
; #pragma unroll
;             for (int i = 0; i < 16; i += 2) { float kl[2][2];
; #pragma unroll
;                 for (int d = 0; d < 2; ++d) { const float kn0 = kb[0][i + d] * ieoff[0], kn1 = kb[1][i + d] * ieoff[1];
;                     ((LAS unsigned*)(lds + OFF_QG))[(t0 + i + d) * (QS / 2) + lane] = pkbf(qa[0][i + d] * eoff[0], qa[1][i + d] * eoff[1]);
;                     ((LAS unsigned*)(lds + OFF_KN))[(t0 + i + d) * (QS / 2) + lane] = pkbf(kn0, kn1);
;                     kl[0][d] = kn0 * eGl[0]; kl[1][d] = kn1 * eGl[1]; }
;                 klp[0][i >> 1] = pkbf(kl[0][0], kl[0][1]); klp[1][i >> 1] = pkbf(kl[1][0], kl[1][1]); }
	ds_read2st64_b64 v[148:151], v110 offset1:1
	ds_read2st64_b64 v[152:155], v110 offset0:2 offset1:3
	v_lshlrev_b32_e32 v52, 16, v33
	v_lshlrev_b32_e32 v32, 16, v62
	v_and_b32_e32 v91, 0xffff0000, v53
	v_and_b32_e32 v53, 0xffff0000, v33
	v_and_b32_e32 v33, 0xffff0000, v62
	s_waitcnt lgkmcnt(1)
	v_cndmask_b32_e64 v62, 1.0, v148, s[8:9]
	v_cndmask_b32_e64 v63, 1.0, v150, s[10:11]
	v_mul_f32_e32 v95, v62, v63
	v_cndmask_b32_e64 v62, 1.0, v149, s[8:9]
	v_cndmask_b32_e64 v63, 1.0, v151, s[10:11]
	s_waitcnt lgkmcnt(0)
	v_cndmask_b32_e64 v161, 1.0, v152, s[12:13]
	v_mul_f32_e32 v101, v62, v63
	v_cndmask_b32_e64 v63, 1.0, v153, s[12:13]
	v_mov_b32_e32 v62, v169
	v_rcp_f32_e32 v164, v160
	v_rcp_f32_e32 v172, v170
	v_rcp_f32_e32 v165, v169
	v_rcp_f32_e32 v173, v171
	v_pk_mul_f32 v[160:161], v[160:161], v[94:95]
	v_pk_mul_f32 v[100:101], v[62:63], v[100:101]
	v_rcp_f32_e32 v94, v161
	v_rcp_f32_e32 v95, v101
	v_pk_mul_f32 v[62:63], v[148:149], v[150:151]
	v_pk_mul_f32 v[148:149], v[152:153], v[154:155]
	v_mov_b32_e32 v150, v160
	v_mov_b32_e32 v151, v100
	v_mov_b32_e32 v100, v161
	v_pk_mul_f32 v[62:63], v[62:63], v[148:149]
	v_mov_b32_e32 v148, v158
	v_mov_b32_e32 v149, v163
	v_pk_mul_f32 v[150:151], v[150:151], v[100:101]
	v_mov_b32_e32 v163, v159
	v_pk_mul_f32 v[152:153], v[170:171], v[156:157]
	v_rcp_f32_e32 v178, v174
	v_rcp_f32_e32 v184, v182
	v_rcp_f32_e32 v179, v175
	v_rcp_f32_e32 v185, v183
	v_pk_mul_f32 v[148:149], v[164:165], v[148:149]
	v_cvt_pk_bf16_f32 v147, v150, v151
	v_pk_mul_f32 v[150:151], v[172:173], v[162:163]
	v_pk_mul_f32 v[152:153], v[152:153], v[100:101]
	v_pk_mul_f32 v[148:149], v[148:149], v[94:95]
	v_pk_mul_f32 v[150:151], v[150:151], v[94:95]
	v_cvt_pk_bf16_f32 v152, v152, v153
	ds_write2_b32 v112, v147, v152 offset1:68
	v_cvt_pk_bf16_f32 v147, v150, v151
	v_mov_b32_e32 v152, v148
	v_mov_b32_e32 v153, v150
	v_mov_b32_e32 v150, v149
	v_pk_mul_f32 v[90:91], v[174:175], v[90:91]
	v_cvt_pk_bf16_f32 v154, v148, v149
	v_add_u32_e32 v155, 0x4400, v112
	v_pk_mul_f32 v[152:153], v[62:63], v[152:153] op_sel_hi:[0,1]
	v_pk_mul_f32 v[150:151], v[62:63], v[150:151] op_sel:[1,0]
	v_pk_mul_f32 v[90:91], v[90:91], v[100:101]
	v_pk_mul_f32 v[78:79], v[182:183], v[78:79]
	ds_write2_b32 v155, v154, v147 offset1:68
	v_cvt_pk_bf16_f32 v148, v152, v153
	v_cvt_pk_bf16_f32 v152, v150, v151
	v_pk_mul_f32 v[150:151], v[178:179], v[166:167]
	v_cvt_pk_bf16_f32 v147, v90, v91
	v_pk_mul_f32 v[90:91], v[184:185], v[176:177]
	v_pk_mul_f32 v[78:79], v[78:79], v[100:101]
	v_rcp_f32_e32 v188, v186
	v_rcp_f32_e32 v189, v187
	v_rcp_f32_e32 v194, v192
	v_rcp_f32_e32 v195, v193
	v_pk_mul_f32 v[150:151], v[150:151], v[94:95]
	v_pk_mul_f32 v[90:91], v[90:91], v[94:95]
	v_cvt_pk_bf16_f32 v78, v78, v79
	v_cvt_pk_bf16_f32 v149, v150, v151
	ds_write2_b32 v112, v147, v78 offset0:136 offset1:204
	v_cvt_pk_bf16_f32 v78, v90, v91
	ds_write2_b32 v155, v149, v78 offset0:136 offset1:204
	v_mov_b32_e32 v78, v150
	v_mov_b32_e32 v79, v90
	v_mov_b32_e32 v90, v151
	v_pk_mul_f32 v[60:61], v[186:187], v[60:61]
	v_pk_mul_f32 v[78:79], v[62:63], v[78:79] op_sel_hi:[0,1]
	v_pk_mul_f32 v[90:91], v[62:63], v[90:91] op_sel:[1,0]
	v_pk_mul_f32 v[60:61], v[60:61], v[100:101]
	v_pk_mul_f32 v[52:53], v[192:193], v[52:53]
	v_cvt_pk_bf16_f32 v149, v78, v79
	v_cvt_pk_bf16_f32 v153, v90, v91
	v_pk_mul_f32 v[78:79], v[188:189], v[180:181]
	v_cvt_pk_bf16_f32 v90, v60, v61
	v_pk_mul_f32 v[60:61], v[194:195], v[190:191]
	v_pk_mul_f32 v[52:53], v[52:53], v[100:101]
	v_rcp_f32_e32 v200, v198
	v_rcp_f32_e32 v204, v202
	v_rcp_f32_e32 v201, v199
	v_rcp_f32_e32 v205, v203
	v_pk_mul_f32 v[78:79], v[78:79], v[94:95]
	v_pk_mul_f32 v[60:61], v[60:61], v[94:95]
	v_cvt_pk_bf16_f32 v52, v52, v53
	v_add_u32_e32 v147, 0x400, v112
	v_cvt_pk_bf16_f32 v91, v78, v79
	ds_write2_b32 v147, v90, v52 offset0:16 offset1:84
	v_cvt_pk_bf16_f32 v52, v60, v61
	v_add_u32_e32 v90, 0x4800, v112
	ds_write2_b32 v90, v91, v52 offset0:16 offset1:84
	v_mov_b32_e32 v52, v78
	v_mov_b32_e32 v53, v60
	v_mov_b32_e32 v60, v79
	v_pk_mul_f32 v[50:51], v[198:199], v[50:51]
	v_pk_mul_f32 v[52:53], v[62:63], v[52:53] op_sel_hi:[0,1]
	v_pk_mul_f32 v[60:61], v[62:63], v[60:61] op_sel:[1,0]
	v_pk_mul_f32 v[50:51], v[50:51], v[100:101]
	v_pk_mul_f32 v[48:49], v[202:203], v[48:49]
	v_cvt_pk_bf16_f32 v150, v52, v53
	v_cvt_pk_bf16_f32 v154, v60, v61
	v_pk_mul_f32 v[52:53], v[200:201], v[108:109]
	v_cvt_pk_bf16_f32 v60, v50, v51
	v_pk_mul_f32 v[50:51], v[204:205], v[196:197]
	v_pk_mul_f32 v[48:49], v[48:49], v[100:101]
	v_rcp_f32_e32 v208, v206
	v_rcp_f32_e32 v210, v106
	v_rcp_f32_e32 v209, v207
	v_rcp_f32_e32 v211, v107
	v_pk_mul_f32 v[52:53], v[52:53], v[94:95]
; #define LAS __attribute__((address_space(3)))
; __device__ __forceinline__ unsigned pkbf(float lo, float hi) { const f32x2_m v = {lo, hi}; const bf16x2_m b = __builtin_convertvector(v, bf16x2_m); return __builtin_bit_cast(unsigned, b); }
; __device__ __forceinline__ void hgrn_unit(LAS unsigned char* lds, int b, int h, int vs, const bf16* QR, const _Float16* LF, const bf16* IO, bf16* OR_) {
;     ...
;             unsigned klp[2][8];
; #pragma unroll
;             for (int i = 0; i < 16; i += 2) { float kl[2][2];
; #pragma unroll
;                 for (int d = 0; d < 2; ++d) { const float kn0 = kb[0][i + d] * ieoff[0], kn1 = kb[1][i + d] * ieoff[1];
;                     ((LAS unsigned*)(lds + OFF_QG))[(t0 + i + d) * (QS / 2) + lane] = pkbf(qa[0][i + d] * eoff[0], qa[1][i + d] * eoff[1]);
;                     ((LAS unsigned*)(lds + OFF_KN))[(t0 + i + d) * (QS / 2) + lane] = pkbf(kn0, kn1);
;                     kl[0][d] = kn0 * eGl[0]; kl[1][d] = kn1 * eGl[1]; }
;                 klp[0][i >> 1] = pkbf(kl[0][0], kl[0][1]); klp[1][i >> 1] = pkbf(kl[1][0], kl[1][1]); }
; #pragma unroll
;             for (int e = 0; e < 2; ++e) { const int k = 2 * lane + e;
;                 *(LAS v4u*)(lds + OFF_KLT + (k * TS + t0) * 2) = (v4u){klp[e][0], klp[e][1], klp[e][2], klp[e][3]};
;                 *(LAS v4u*)(lds + OFF_KLT + (k * TS + t0 + 8) * 2) = (v4u){klp[e][4], klp[e][5], klp[e][6], klp[e][7]}; }
;             if (ew == 0) ((LAS f32x2_m*)(lds + OFF_GL))[lane] = (f32x2_m){eGl[0], eGl[1]};
	v_pk_mul_f32 v[50:51], v[50:51], v[94:95]
	v_cvt_pk_bf16_f32 v48, v48, v49
	v_lshlrev_b32_e32 v46, 16, v65
	v_and_b32_e32 v47, 0xffff0000, v65
	v_cvt_pk_bf16_f32 v61, v52, v53
	ds_write2_b32 v147, v60, v48 offset0:152 offset1:220
	v_cvt_pk_bf16_f32 v48, v50, v51
	ds_write2_b32 v90, v61, v48 offset0:152 offset1:220
	v_mov_b32_e32 v48, v52
	v_mov_b32_e32 v49, v50
	v_mov_b32_e32 v50, v53
	v_pk_mul_f32 v[46:47], v[206:207], v[46:47]
	v_pk_mul_f32 v[48:49], v[62:63], v[48:49] op_sel_hi:[0,1]
	v_pk_mul_f32 v[50:51], v[62:63], v[50:51] op_sel:[1,0]
	v_pk_mul_f32 v[46:47], v[46:47], v[100:101]
	v_pk_mul_f32 v[44:45], v[106:107], v[44:45]
	v_cvt_pk_bf16_f32 v151, v48, v49
	v_cvt_pk_bf16_f32 v155, v50, v51
	v_pk_mul_f32 v[48:49], v[208:209], v[104:105]
	v_cvt_pk_bf16_f32 v50, v46, v47
	v_pk_mul_f32 v[46:47], v[210:211], v[102:103]
	v_pk_mul_f32 v[44:45], v[44:45], v[100:101]
	v_rcp_f32_e32 v98, v92
	v_rcp_f32_e32 v96, v88
	v_rcp_f32_e32 v99, v93
	v_rcp_f32_e32 v97, v89
	v_pk_mul_f32 v[48:49], v[48:49], v[94:95]
	v_pk_mul_f32 v[46:47], v[46:47], v[94:95]
	v_cvt_pk_bf16_f32 v44, v44, v45
	v_add_u32_e32 v52, 0x800, v112
	v_cvt_pk_bf16_f32 v51, v48, v49
	ds_write2_b32 v52, v50, v44 offset0:32 offset1:100
	v_cvt_pk_bf16_f32 v44, v46, v47
	v_add_u32_e32 v50, 0x4c00, v112
	ds_write2_b32 v50, v51, v44 offset0:32 offset1:100
	v_mov_b32_e32 v44, v48
	v_mov_b32_e32 v45, v46
	v_mov_b32_e32 v46, v49
	v_pk_mul_f32 v[42:43], v[92:93], v[42:43]
	v_pk_mul_f32 v[44:45], v[62:63], v[44:45] op_sel_hi:[0,1]
	v_pk_mul_f32 v[46:47], v[62:63], v[46:47] op_sel:[1,0]
	v_pk_mul_f32 v[42:43], v[42:43], v[100:101]
	v_pk_mul_f32 v[40:41], v[88:89], v[40:41]
	v_cvt_pk_bf16_f32 v44, v44, v45
	v_cvt_pk_bf16_f32 v48, v46, v47
	v_pk_mul_f32 v[46:47], v[98:99], v[86:87]
	v_cvt_pk_bf16_f32 v45, v42, v43
	v_pk_mul_f32 v[42:43], v[96:97], v[82:83]
	v_pk_mul_f32 v[40:41], v[40:41], v[100:101]
	v_rcp_f32_e32 v84, v76
	v_rcp_f32_e32 v80, v74
	v_rcp_f32_e32 v85, v77
	v_rcp_f32_e32 v81, v75
	v_pk_mul_f32 v[46:47], v[46:47], v[94:95]
	v_pk_mul_f32 v[42:43], v[42:43], v[94:95]
	v_cvt_pk_bf16_f32 v40, v40, v41
	v_cvt_pk_bf16_f32 v49, v46, v47
	ds_write2_b32 v52, v45, v40 offset0:168 offset1:236
	v_cvt_pk_bf16_f32 v40, v42, v43
	ds_write2_b32 v50, v49, v40 offset0:168 offset1:236
	v_mov_b32_e32 v40, v46
	v_mov_b32_e32 v41, v42
	v_mov_b32_e32 v42, v47
	v_pk_mul_f32 v[38:39], v[76:77], v[38:39]
	v_pk_mul_f32 v[40:41], v[62:63], v[40:41] op_sel_hi:[0,1]
	v_pk_mul_f32 v[42:43], v[62:63], v[42:43] op_sel:[1,0]
	v_pk_mul_f32 v[38:39], v[38:39], v[100:101]
	v_pk_mul_f32 v[36:37], v[74:75], v[36:37]
	v_cvt_pk_bf16_f32 v45, v40, v41
	v_cvt_pk_bf16_f32 v49, v42, v43
	v_pk_mul_f32 v[40:41], v[84:85], v[72:73]
	v_cvt_pk_bf16_f32 v42, v38, v39
	v_pk_mul_f32 v[38:39], v[80:81], v[70:71]
	v_pk_mul_f32 v[36:37], v[36:37], v[100:101]
	v_rcp_f32_e32 v68, v66
	v_rcp_f32_e32 v64, v58
	v_rcp_f32_e32 v69, v67
	v_rcp_f32_e32 v65, v59
	v_pk_mul_f32 v[40:41], v[40:41], v[94:95]
	v_pk_mul_f32 v[38:39], v[38:39], v[94:95]
	v_cvt_pk_bf16_f32 v36, v36, v37
	v_add_u32_e32 v47, 0xc00, v112
	v_cvt_pk_bf16_f32 v43, v40, v41
	ds_write2_b32 v47, v42, v36 offset0:48 offset1:116
	v_cvt_pk_bf16_f32 v36, v38, v39
	v_add_u32_e32 v42, 0x5000, v112
	ds_write2_b32 v42, v43, v36 offset0:48 offset1:116
	v_mov_b32_e32 v36, v40
	v_mov_b32_e32 v37, v38
	v_mov_b32_e32 v38, v41
	v_pk_mul_f32 v[34:35], v[66:67], v[34:35]
	v_pk_mul_f32 v[36:37], v[62:63], v[36:37] op_sel_hi:[0,1]
	v_pk_mul_f32 v[38:39], v[62:63], v[38:39] op_sel:[1,0]
	v_pk_mul_f32 v[34:35], v[34:35], v[100:101]
	v_pk_mul_f32 v[32:33], v[58:59], v[32:33]
	v_cvt_pk_bf16_f32 v46, v36, v37
	v_cvt_pk_bf16_f32 v50, v38, v39
	v_pk_mul_f32 v[36:37], v[68:69], v[56:57]
	v_cvt_pk_bf16_f32 v38, v34, v35
	v_pk_mul_f32 v[34:35], v[64:65], v[54:55]
	v_pk_mul_f32 v[32:33], v[32:33], v[100:101]
	v_pk_mul_f32 v[36:37], v[36:37], v[94:95]
	v_pk_mul_f32 v[34:35], v[34:35], v[94:95]
	v_cvt_pk_bf16_f32 v32, v32, v33
	v_cvt_pk_bf16_f32 v39, v36, v37
	ds_write2_b32 v47, v38, v32 offset0:184 offset1:252
	v_cvt_pk_bf16_f32 v32, v34, v35
	v_mov_b32_e32 v33, v34
	v_mov_b32_e32 v34, v37
	ds_write2_b32 v42, v39, v32 offset0:184 offset1:252
	v_mov_b32_e32 v32, v36
	v_pk_mul_f32 v[34:35], v[62:63], v[34:35] op_sel:[1,0]
	v_pk_mul_f32 v[32:33], v[62:63], v[32:33] op_sel_hi:[0,1]
	v_cvt_pk_bf16_f32 v51, v34, v35
	s_andn2_b64 vcc, exec, s[14:15]
	v_cvt_pk_bf16_f32 v47, v32, v33
	ds_write_b128 v113, v[148:151] offset:34816
	ds_write_b128 v113, v[44:47] offset:34832
	ds_write_b128 v113, v[152:155] offset:34960
	ds_write_b128 v113, v[48:51] offset:34976
	s_cbranch_vccnz .LBB0_1548
	ds_write_b64 v111, v[62:63]
	s_branch .LBB0_1548
